# NSA score tiles: fixed softmax reference (-16) dropped in all four branch loops (each branch is normalised by its own sum; logits bounded by the q/k RMS norms): 108 adds removed, 20 became moves
# baseline (speedup 1.0000x reference)
.LBB0_378:
	s_ashr_i32 s19, s18, 31
	s_lshl_b64 s[6:7], s[18:19], 10
	v_lshl_add_u64 v[42:43], v[140:141], 0, s[6:7]
	s_add_i32 s6, s18, -2
	s_ashr_i32 s7, s6, 31
	s_lshl_b64 s[6:7], s[6:7], 10
	v_lshl_add_u64 v[62:63], v[140:141], 0, s[6:7]
	global_load_dwordx4 v[38:41], v[42:43], off
	s_nop 0
	global_load_dwordx4 v[42:45], v[42:43], off offset:1024
	v_add_u32_e32 v79, 0x70, v37
	global_load_dwordx4 v[58:61], v[62:63], off
	v_add_u32_e32 v87, 48, v37
	global_load_dwordx4 v[62:65], v[62:63], off offset:1024
	v_add_u32_e32 v81, 0x60, v37
	v_cvt_f32_i32_e32 v79, v79
	v_cvt_f32_i32_e32 v87, v87
	v_add_u32_e32 v83, 0x50, v37
	v_cvt_f32_i32_e32 v81, v81
	v_add_u32_e32 v85, 64, v37
	v_cvt_f32_i32_e32 v83, v83
	v_cvt_f32_i32_e32 v85, v85
	v_add_u32_e32 v89, 32, v37
	v_add_u32_e32 v91, 16, v37
	v_cvt_f32_i32_e32 v89, v89
	v_subrev_u32_e32 v86, 48, v36
	v_cvt_f32_i32_e32 v92, v37
	v_add_u32_e32 v78, 0xffffff90, v36
	v_add_u32_e32 v80, 0xffffffa0, v36
	v_cmp_gt_i32_e32 vcc, v86, v134
	v_add_u32_e32 v82, 0xffffffb0, v36
	v_cmp_gt_i32_e64 s[12:13], v80, v134
	v_subrev_u32_e32 v84, 64, v36
	v_cmp_gt_i32_e64 s[14:15], v82, v134
	v_cmp_gt_i32_e64 s[16:17], v84, v134
	v_subrev_u32_e32 v88, 32, v36
	v_add_u32_e32 v90, -16, v36
	v_cmp_gt_i32_e64 s[6:7], v88, v134
	v_cmp_gt_i32_e64 s[8:9], v90, v134
	v_cmp_gt_i32_e64 s[10:11], v36, v134
	s_add_i32 s20, s20, -1
	s_add_i32 s18, s18, 4
	v_add_u32_e32 v37, 0xfffffe00, v37
	s_cmp_lg_u32 s20, 0
	v_add_u32_e32 v36, 0x200, v36
	s_waitcnt vmcnt(3)
	v_mfma_f32_16x16x32_bf16 v[46:49], v[38:41], v[0:3], 0
	v_mfma_f32_16x16x32_bf16 v[50:53], v[38:41], v[8:11], 0
	v_mfma_f32_16x16x32_bf16 v[54:57], v[38:41], v[16:19], 0
	v_mfma_f32_16x16x32_bf16 v[38:41], v[38:41], v[24:27], 0
	s_waitcnt vmcnt(1)
	v_mfma_f32_16x16x32_bf16 v[66:69], v[58:61], v[0:3], 0
	v_mfma_f32_16x16x32_bf16 v[70:73], v[58:61], v[8:11], 0
	v_mfma_f32_16x16x32_bf16 v[74:77], v[58:61], v[16:19], 0
	v_mfma_f32_16x16x32_bf16 v[58:61], v[58:61], v[24:27], 0
	v_mfma_f32_16x16x32_bf16 v[46:49], v[42:45], v[4:7], v[46:49]
	v_mfma_f32_16x16x32_bf16 v[50:53], v[42:45], v[12:15], v[50:53]
	v_mfma_f32_16x16x32_bf16 v[54:57], v[42:45], v[20:23], v[54:57]
	s_nop 5
	v_fma_f32 v46, -v170, v87, v46
	v_mfma_f32_16x16x32_bf16 v[38:41], v[42:45], v[28:31], v[38:41]
	v_fma_f32 v50, -v171, v87, v50
	v_fma_f32 v54, -v172, v87, v54
	s_waitcnt vmcnt(0)
	v_mfma_f32_16x16x32_bf16 v[42:45], v[62:65], v[4:7], v[66:69]
	v_exp_f32_e32 v46, v46
	s_nop 1
	s_nop 0
	v_fma_f32 v38, -v173, v87, v38
	v_mfma_f32_16x16x32_bf16 v[66:69], v[62:65], v[12:15], v[70:73]
	v_exp_f32_e32 v50, v50
	s_nop 0
	v_mfma_f32_16x16x32_bf16 v[70:73], v[62:65], v[20:23], v[74:77]
	v_fma_f32 v42, -v170, v79, v42
	v_fma_f32 v43, -v170, v81, v43
	v_mfma_f32_16x16x32_bf16 v[58:61], v[62:65], v[28:31], v[58:61]
	s_nop 1
	v_mov_b32_e32 v62, v66
	s_nop 2
	v_mov_b32_e32 v63, v67
	v_fma_f32 v62, -v171, v79, v62
	v_fma_f32 v66, -v172, v79, v70
	v_fma_f32 v58, -v173, v79, v58
	v_mov_b32_e32 v64, v68
	v_fma_f32 v63, -v171, v81, v63
	v_fma_f32 v67, -v172, v81, v71
	v_exp_f32_e32 v54, v54
	v_fma_f32 v59, -v173, v81, v59
	v_exp_f32_e32 v38, v38
	v_exp_f32_e32 v42, v42
	v_exp_f32_e32 v62, v62
	v_exp_f32_e32 v66, v66
	v_exp_f32_e32 v58, v58
	v_cvt_f32_i32_e32 v74, v91
	v_mov_b32_e32 v65, v69
	v_fma_f32 v44, -v170, v83, v44
	v_fma_f32 v64, -v171, v83, v64
	v_fma_f32 v68, -v172, v83, v72
	v_fma_f32 v60, -v173, v83, v60
	v_exp_f32_e32 v43, v43
	v_exp_f32_e32 v63, v63
	v_exp_f32_e32 v67, v67
	v_exp_f32_e32 v59, v59
	v_fma_f32 v45, -v170, v85, v45
	v_fma_f32 v65, -v171, v85, v65
	v_fma_f32 v69, -v172, v85, v73
	v_fma_f32 v61, -v173, v85, v61
	v_exp_f32_e32 v44, v44
	v_exp_f32_e32 v64, v64
	v_exp_f32_e32 v68, v68
	v_exp_f32_e32 v60, v60
	v_exp_f32_e32 v45, v45
	v_exp_f32_e32 v65, v65
	v_exp_f32_e32 v69, v69
	v_exp_f32_e32 v61, v61
	v_fma_f32 v47, -v170, v89, v47
	v_fma_f32 v51, -v171, v89, v51
	v_fma_f32 v55, -v172, v89, v55
	v_fma_f32 v39, -v173, v89, v39
	v_cndmask_b32_e64 v46, v46, 0, vcc
	v_cndmask_b32_e64 v50, v50, 0, vcc
	v_cndmask_b32_e64 v54, v54, 0, vcc
	v_cndmask_b32_e64 v38, v38, 0, vcc
	v_add_f32_e32 v42, 0, v42
	v_add_f32_e32 v62, 0, v62
	v_add_f32_e32 v66, 0, v66
	v_add_f32_e32 v58, 0, v58
	v_cmp_gt_i32_e32 vcc, v78, v134
	v_fma_f32 v48, -v170, v74, v48
	v_fma_f32 v52, -v171, v74, v52
	v_fma_f32 v56, -v172, v74, v56
	v_fma_f32 v40, -v173, v74, v40
	v_exp_f32_e32 v47, v47
	v_exp_f32_e32 v51, v51
	v_exp_f32_e32 v55, v55
	v_exp_f32_e32 v39, v39
	v_cndmask_b32_e64 v43, v43, 0, s[12:13]
	v_cndmask_b32_e64 v63, v63, 0, s[12:13]
	v_cndmask_b32_e64 v67, v67, 0, s[12:13]
	v_cndmask_b32_e64 v59, v59, 0, s[12:13]
	v_cndmask_b32_e64 v42, v42, 0, vcc
	v_cndmask_b32_e64 v62, v62, 0, vcc
	v_cndmask_b32_e64 v66, v66, 0, vcc
	v_cndmask_b32_e64 v58, v58, 0, vcc
	v_fma_f32 v49, -v170, v92, v49
	v_fma_f32 v53, -v171, v92, v53
	v_fma_f32 v57, -v172, v92, v57
	v_fma_f32 v41, -v173, v92, v41
	v_exp_f32_e32 v48, v48
	v_exp_f32_e32 v52, v52
	v_exp_f32_e32 v56, v56
	v_exp_f32_e32 v40, v40
	v_cndmask_b32_e64 v44, v44, 0, s[14:15]
	v_cndmask_b32_e64 v64, v64, 0, s[14:15]
	v_cndmask_b32_e64 v68, v68, 0, s[14:15]
	v_cndmask_b32_e64 v60, v60, 0, s[14:15]
	v_add_f32_e32 v42, v43, v42
	v_add_f32_e32 v43, v63, v62
	v_add_f32_e32 v62, v67, v66
	v_add_f32_e32 v58, v59, v58
	v_exp_f32_e32 v49, v49
	v_exp_f32_e32 v53, v53
	v_exp_f32_e32 v57, v57
	v_exp_f32_e32 v41, v41
	v_cndmask_b32_e64 v45, v45, 0, s[16:17]
	v_cndmask_b32_e64 v65, v65, 0, s[16:17]
	v_cndmask_b32_e64 v69, v69, 0, s[16:17]
	v_cndmask_b32_e64 v61, v61, 0, s[16:17]
	v_add_f32_e32 v42, v44, v42
	v_add_f32_e32 v43, v64, v43
	v_add_f32_e32 v44, v68, v62
	v_add_f32_e32 v58, v60, v58
	v_add_f32_e32 v42, v45, v42
	v_add_f32_e32 v43, v65, v43
	v_add_f32_e32 v44, v69, v44
	v_add_f32_e32 v45, v61, v58
	v_cndmask_b32_e64 v47, v47, 0, s[6:7]
	v_cndmask_b32_e64 v51, v51, 0, s[6:7]
	v_cndmask_b32_e64 v55, v55, 0, s[6:7]
	v_cndmask_b32_e64 v39, v39, 0, s[6:7]
	v_add_f32_e32 v42, v46, v42
	v_add_f32_e32 v43, v50, v43
	v_add_f32_e32 v44, v54, v44
	v_add_f32_e32 v38, v38, v45
	v_cndmask_b32_e64 v48, v48, 0, s[8:9]
	v_cndmask_b32_e64 v52, v52, 0, s[8:9]
	v_cndmask_b32_e64 v56, v56, 0, s[8:9]
	v_cndmask_b32_e64 v40, v40, 0, s[8:9]
	v_add_f32_e32 v42, v47, v42
	v_add_f32_e32 v43, v51, v43
	v_add_f32_e32 v44, v55, v44
	v_add_f32_e32 v38, v39, v38
	v_cndmask_b32_e64 v49, v49, 0, s[10:11]
	v_cndmask_b32_e64 v53, v53, 0, s[10:11]
	v_cndmask_b32_e64 v57, v57, 0, s[10:11]
	v_cndmask_b32_e64 v41, v41, 0, s[10:11]
	v_add_f32_e32 v39, v48, v42
	v_add_f32_e32 v42, v52, v43
	v_add_f32_e32 v43, v56, v44
	v_add_f32_e32 v38, v40, v38
	v_add_f32_e32 v39, v49, v39
	v_add_f32_e32 v40, v53, v42
	v_add_f32_e32 v42, v57, v43
	v_add_f32_e32 v38, v41, v38
	v_add_f32_e32 v35, v35, v39
	v_add_f32_e32 v32, v32, v40
	v_add_f32_e32 v34, v34, v42
	v_add_f32_e32 v33, v33, v38
	s_cbranch_scc1 .LBB0_378
	ds_bpermute_b32 v36, v167, v35
	ds_bpermute_b32 v37, v167, v32
	v_lshlrev_b32_e32 v156, 1, v168
	v_mov_b32_e32 v129, v134
	s_mov_b32 s20, 3
	s_waitcnt lgkmcnt(1)
	v_add_f32_e32 v35, v35, v36
	s_waitcnt lgkmcnt(0)
	v_add_f32_e32 v36, v32, v37
	ds_bpermute_b32 v37, v166, v35
	ds_bpermute_b32 v38, v166, v36
	v_mov_b32_e32 v32, 0
	v_mov_b32_e32 v43, v32
	v_mov_b32_e32 v44, v32
	s_waitcnt lgkmcnt(1)
	v_add_f32_e32 v35, v35, v37
	v_div_scale_f32 v37, s[6:7], v35, v35, 1.0
	s_waitcnt lgkmcnt(0)
	v_add_f32_e32 v36, v36, v38
	v_rcp_f32_e32 v38, v37
	v_div_scale_f32 v39, vcc, 1.0, v35, 1.0
	v_div_scale_f32 v40, s[6:7], v36, v36, 1.0
	v_fma_f32 v41, -v37, v38, 1.0
	v_fmac_f32_e32 v38, v41, v38
	v_mul_f32_e32 v41, v39, v38
	v_fma_f32 v42, -v37, v41, v39
	v_fmac_f32_e32 v41, v42, v38
	v_fma_f32 v37, -v37, v41, v39
	v_div_fmas_f32 v37, v37, v38, v41
	v_rcp_f32_e32 v38, v40
	v_div_fixup_f32 v37, v37, v35, 1.0
	v_cmp_lt_f32_e32 vcc, 0, v35
	v_mov_b32_e32 v42, v32
	v_fma_f32 v35, -v40, v38, 1.0
	v_fmac_f32_e32 v38, v35, v38
	ds_bpermute_b32 v35, v167, v34
	v_cndmask_b32_e32 v142, 0, v37, vcc
	v_div_scale_f32 v37, vcc, 1.0, v36, 1.0
	v_mul_f32_e32 v39, v37, v38
	s_waitcnt lgkmcnt(0)
	v_add_f32_e32 v34, v34, v35
	ds_bpermute_b32 v35, v166, v34
	v_fma_f32 v41, -v40, v39, v37
	v_fmac_f32_e32 v39, v41, v38
	v_fma_f32 v37, -v40, v39, v37
	v_div_fmas_f32 v37, v37, v38, v39
	s_waitcnt lgkmcnt(0)
	v_add_f32_e32 v34, v34, v35
	v_div_scale_f32 v35, s[6:7], v34, v34, 1.0
	v_rcp_f32_e32 v38, v35
	v_div_fixup_f32 v37, v37, v36, 1.0
	v_cmp_lt_f32_e32 vcc, 0, v36
	v_mov_b32_e32 v143, v142
	v_fma_f32 v36, -v35, v38, 1.0
	v_fmac_f32_e32 v38, v36, v38
	ds_bpermute_b32 v36, v167, v33
	v_cndmask_b32_e32 v144, 0, v37, vcc
	v_div_scale_f32 v37, vcc, 1.0, v34, 1.0
	v_mul_f32_e32 v39, v37, v38
	s_waitcnt lgkmcnt(0)
	v_add_f32_e32 v33, v33, v36
	ds_bpermute_b32 v36, v166, v33
	v_fma_f32 v40, -v35, v39, v37
	v_fmac_f32_e32 v39, v40, v38
	v_fma_f32 v35, -v35, v39, v37
	v_div_fmas_f32 v35, v35, v38, v39
	s_waitcnt lgkmcnt(0)
	v_add_f32_e32 v33, v33, v36
	v_div_scale_f32 v36, s[6:7], v33, v33, 1.0
	v_rcp_f32_e32 v37, v36
	v_div_fixup_f32 v35, v35, v34, 1.0
	v_cmp_lt_f32_e32 vcc, 0, v34
	s_add_u32 s6, s81, s1
	v_fma_f32 v34, -v36, v37, 1.0
	v_cndmask_b32_e32 v146, 0, v35, vcc
	v_fmac_f32_e32 v37, v34, v37
	v_div_scale_f32 v34, vcc, 1.0, v33, 1.0
	v_mul_f32_e32 v35, v34, v37
	v_fma_f32 v38, -v36, v35, v34
	v_fmac_f32_e32 v35, v38, v37
	v_fma_f32 v34, -v36, v35, v34
	v_div_fmas_f32 v34, v34, v37, v35
	v_div_fixup_f32 v34, v34, v33, 1.0
	v_cmp_lt_f32_e32 vcc, 0, v33
	s_addc_u32 s7, s82, 0
	v_lshlrev_b32_e32 v36, 4, v128
	v_cndmask_b32_e32 v148, 0, v34, vcc
	v_lshl_add_u64 v[34:35], v[138:139], 4, s[6:7]
	v_mov_b32_e32 v37, v133
	v_lshlrev_b32_e32 v33, 8, v128
	v_lshl_add_u64 v[150:151], v[34:35], 0, v[36:37]
	v_add3_u32 v155, s79, v33, v130
	v_mov_b32_e32 v145, v144
	v_mov_b32_e32 v147, v146
	v_mov_b32_e32 v149, v148
	v_mov_b32_e32 v33, v32
	v_mov_b32_e32 v34, v32
	v_mov_b32_e32 v35, v32
	v_mov_b32_e32 v36, v32
	v_mov_b32_e32 v37, v32
	v_mov_b32_e32 v38, v32
	v_mov_b32_e32 v39, v32
	v_mov_b32_e32 v40, v32
	v_mov_b32_e32 v41, v32
	v_mov_b32_e32 v45, v32
	v_mov_b32_e32 v46, v32
	v_mov_b32_e32 v47, v32
	v_mov_b32_e32 v48, v32
	v_mov_b32_e32 v49, v32
	v_mov_b32_e32 v50, v32
	v_mov_b32_e32 v51, v32
	v_mov_b32_e32 v52, v32
	v_mov_b32_e32 v53, v32
	v_mov_b32_e32 v54, v32
	v_mov_b32_e32 v55, v32
	v_mov_b32_e32 v56, v32
	v_mov_b32_e32 v57, v32
	v_mov_b32_e32 v58, v32
	v_mov_b32_e32 v59, v32
	v_mov_b32_e32 v60, v32
	v_mov_b32_e32 v61, v32
	v_mov_b32_e32 v62, v32
	v_mov_b32_e32 v63, v32
	v_mov_b32_e32 v64, v32
	v_mov_b32_e32 v65, v32
	v_mov_b32_e32 v66, v32
	v_mov_b32_e32 v67, v32
	v_mov_b32_e32 v68, v32
	v_mov_b32_e32 v69, v32
	v_mov_b32_e32 v70, v32
	v_mov_b32_e32 v71, v32
	v_mov_b32_e32 v72, v32
	v_mov_b32_e32 v73, v32
	v_mov_b32_e32 v74, v32
	v_mov_b32_e32 v75, v32
	v_mov_b32_e32 v76, v32
	v_mov_b32_e32 v77, v32
	v_mov_b32_e32 v78, v32
	v_mov_b32_e32 v79, v32
	v_mov_b32_e32 v80, v32
	v_mov_b32_e32 v81, v32
	v_mov_b32_e32 v82, v32
	v_mov_b32_e32 v83, v32
	v_mov_b32_e32 v84, v32
	v_mov_b32_e32 v85, v32
	v_mov_b32_e32 v86, v32
	v_mov_b32_e32 v87, v32
	v_mov_b32_e32 v88, v32
	v_mov_b32_e32 v89, v32
	v_mov_b32_e32 v90, v32
	v_mov_b32_e32 v91, v32
	v_mov_b32_e32 v92, v32
	v_mov_b32_e32 v93, v32
	v_mov_b32_e32 v94, v32
	v_mov_b32_e32 v95, v32
	s_branch .LBB0_381

.LBB0_381:
	s_add_i32 s6, s20, -3
	s_ashr_i32 s7, s6, 31
	s_lshl_b64 s[8:9], s[6:7], 10
	v_lshl_add_u64 v[96:97], v[140:141], 0, s[8:9]
	global_load_dwordx4 v[112:115], v[96:97], off
	s_add_i32 s8, s20, -1
	s_ashr_i32 s9, s8, 31
	s_lshl_b64 s[10:11], s[8:9], 10
	v_lshl_add_u64 v[98:99], v[140:141], 0, s[10:11]
	global_load_dwordx4 v[108:111], v[98:99], off
	global_load_dwordx4 v[116:119], v[96:97], off offset:1024
	global_load_dwordx4 v[104:107], v[98:99], off offset:1024
	v_or_b32_e32 v160, 31, v153
	v_or_b32_e32 v176, 47, v153
	v_add_u32_e32 v120, 64, v154
	v_sub_u32_e32 v124, v134, v160
	v_sub_u32_e32 v125, v134, v176
	v_cvt_f32_i32_e32 v208, v120
	v_cvt_f32_i32_e32 v209, v124
	v_cvt_f32_i32_e32 v210, v125
	v_or_b32_e32 v159, 0x5f, v153
	v_or_b32_e32 v161, 0x6f, v153
	v_or_b32_e32 v177, 0x7f, v153
	v_or_b32_e32 v186, 63, v153
	v_sub_u32_e32 v175, v134, v159
	v_sub_u32_e32 v174, v134, v186
	v_sub_u32_e32 v178, v134, v161
	v_sub_u32_e32 v179, v134, v177
	v_cvt_f32_i32_e32 v212, v175
	v_cvt_f32_i32_e32 v180, v154
	v_cvt_f32_i32_e32 v211, v174
	v_cvt_f32_i32_e32 v213, v178
	v_cvt_f32_i32_e32 v214, v179
	s_mov_b32 s7, s49
	s_lshl_b64 s[6:7], s[6:7], 10
	s_add_i32 s48, s20, -2
	v_lshl_add_u64 v[96:97], v[150:151], 0, s[6:7]
	s_lshl_b64 s[6:7], s[48:49], 10
	s_mov_b32 s9, s49
	v_lshl_add_u64 v[100:101], v[150:151], 0, s[6:7]
	v_add_u32_e32 v157, 0x4f, v153
	v_add_u32_e32 v158, 0x8f, v153
	s_lshl_b64 s[6:7], s[8:9], 10
	v_cmp_gt_i32_e64 s[12:13], v159, v129
	v_cmp_gt_i32_e64 s[14:15], v160, v134
	s_mov_b32 s21, s49
	v_lshl_add_u64 v[174:175], v[150:151], 0, s[6:7]
	v_cmp_gt_i32_e64 s[16:17], v161, v129
	v_cmp_gt_i32_e64 s[18:19], v176, v134
	v_cmp_gt_i32_e32 vcc, v177, v129
	v_cmp_gt_i32_e64 s[6:7], v186, v134
	v_cmp_gt_i32_e64 s[8:9], v158, v129
	v_cmp_gt_i32_e64 s[10:11], v157, v134
	s_lshl_b64 s[24:25], s[20:21], 10
	global_load_dwordx4 v[96:99], v[96:97], off
	s_waitcnt vmcnt(3)
	v_mfma_f32_16x16x32_bf16 v[124:127], v[108:111], v[0:3], 0
	global_load_dwordx4 v[100:103], v[100:101], off
	v_mfma_f32_16x16x32_bf16 v[120:123], v[112:115], v[0:3], 0
	s_waitcnt vmcnt(3)
	v_mfma_f32_16x16x32_bf16 v[120:123], v[116:119], v[4:7], v[120:123]
	s_waitcnt vmcnt(2)
	v_mfma_f32_16x16x32_bf16 v[124:127], v[104:107], v[4:7], v[124:127]
	s_nop 5
	s_nop 0
	v_fma_f32 v120, -v170, v209, v120
	v_fma_f32 v124, -v170, v212, v124
	v_fma_f32 v123, -v170, v208, v123
	v_fma_f32 v127, -v170, v180, v127
	v_fma_f32 v121, -v170, v210, v121
	v_fma_f32 v122, -v170, v211, v122
	v_fma_f32 v125, -v170, v213, v125
	v_fma_f32 v126, -v170, v214, v126
	v_exp_f32_e32 v120, v120
	v_exp_f32_e32 v124, v124
	v_exp_f32_e32 v123, v123
	v_exp_f32_e32 v127, v127
	v_exp_f32_e32 v121, v121
	v_exp_f32_e32 v122, v122
	v_exp_f32_e32 v125, v125
	v_exp_f32_e32 v126, v126
	v_cndmask_b32_e64 v179, v124, 0, s[12:13]
	v_cndmask_b32_e64 v178, v120, 0, s[14:15]
	v_cndmask_b32_e64 v185, v125, 0, s[16:17]
	v_cndmask_b32_e64 v184, v121, 0, s[18:19]
	v_cndmask_b32_e64 v187, v126, 0, vcc
	v_cndmask_b32_e64 v186, v122, 0, s[6:7]
	v_cndmask_b32_e64 v189, v127, 0, s[8:9]
	v_cndmask_b32_e64 v188, v123, 0, s[10:11]
	v_mul_f32_e32 v120, v142, v178
	v_mul_f32_e32 v121, v143, v179
	v_mul_f32_e32 v122, v142, v184
	v_mul_f32_e32 v123, v143, v185
	v_mul_f32_e32 v124, v142, v186
	v_mul_f32_e32 v125, v143, v187
	v_mul_f32_e32 v126, v142, v188
	v_mul_f32_e32 v127, v143, v189
	v_cvt_pk_bf16_f32 v158, v120, v122
	v_cvt_pk_bf16_f32 v160, v121, v123
	v_lshl_add_u64 v[120:121], v[150:151], 0, s[24:25]
	v_cvt_pk_bf16_f32 v159, v124, v126
	v_cvt_pk_bf16_f32 v161, v125, v127
	global_load_dwordx4 v[124:127], v[174:175], off
	s_waitcnt vmcnt(2)
	v_mfma_f32_16x16x32_bf16 v[92:95], v[96:99], v[158:161], v[92:95]
	global_load_dwordx4 v[120:123], v[120:121], off
	s_waitcnt vmcnt(2)
	v_mfma_f32_16x16x32_bf16 v[88:91], v[100:103], v[158:161], v[88:91]
	v_mfma_f32_16x16x32_bf16 v[174:177], v[108:111], v[8:11], 0
	s_waitcnt vmcnt(1)
	v_mfma_f32_16x16x32_bf16 v[84:87], v[124:127], v[158:161], v[84:87]
	s_waitcnt vmcnt(0)
	v_mfma_f32_16x16x32_bf16 v[80:83], v[120:123], v[158:161], v[80:83]
	v_mfma_f32_16x16x32_bf16 v[158:161], v[112:115], v[8:11], 0
	v_mfma_f32_16x16x32_bf16 v[158:161], v[116:119], v[12:15], v[158:161]
	s_nop 7
	v_mov_b32_e32 v157, v158
	v_fma_f32 v158, -v171, v210, v159
	v_exp_f32_e32 v192, v158
	v_fma_f32 v158, -v171, v211, v160
	v_exp_f32_e32 v194, v158
	v_fma_f32 v158, -v171, v208, v161
	v_exp_f32_e32 v196, v158
	v_mfma_f32_16x16x32_bf16 v[158:161], v[104:107], v[12:15], v[174:177]
	v_fma_f32 v157, -v171, v209, v157
	v_exp_f32_e32 v157, v157
	v_cndmask_b32_e64 v194, v194, 0, s[6:7]
	v_cndmask_b32_e64 v192, v192, 0, s[18:19]
	v_cndmask_b32_e64 v196, v196, 0, s[10:11]
	s_nop 2
	v_fma_f32 v158, -v171, v212, v158
	v_exp_f32_e32 v158, v158
	v_cndmask_b32_e64 v190, v157, 0, s[14:15]
	v_cndmask_b32_e64 v191, v158, 0, s[12:13]
	v_fma_f32 v157, -v171, v214, v160
	v_fma_f32 v159, -v171, v213, v159
	v_exp_f32_e32 v157, v157
	v_fma_f32 v158, -v171, v180, v161
	v_exp_f32_e32 v159, v159
	v_exp_f32_e32 v158, v158
	v_cndmask_b32_e64 v195, v157, 0, vcc
	v_mul_f32_e32 v160, v144, v194
	v_mul_f32_e32 v161, v145, v195
	v_cndmask_b32_e64 v193, v159, 0, s[16:17]
	v_cndmask_b32_e64 v197, v158, 0, s[8:9]
	v_mul_f32_e32 v174, v144, v190
	v_mul_f32_e32 v175, v145, v191
	v_mul_f32_e32 v176, v144, v192
	v_mul_f32_e32 v177, v145, v193
	v_mul_f32_e32 v198, v144, v196
	v_mul_f32_e32 v199, v145, v197
	v_cvt_pk_bf16_f32 v158, v174, v176
	s_nop 0
	v_cvt_pk_bf16_f32 v159, v160, v198
	v_cvt_pk_bf16_f32 v160, v175, v177
	v_cvt_pk_bf16_f32 v161, v161, v199
	v_mfma_f32_16x16x32_bf16 v[174:177], v[108:111], v[16:19], 0
	s_nop 0
	v_mfma_f32_16x16x32_bf16 v[76:79], v[96:99], v[158:161], v[76:79]
	v_mfma_f32_16x16x32_bf16 v[72:75], v[100:103], v[158:161], v[72:75]
	v_mfma_f32_16x16x32_bf16 v[68:71], v[124:127], v[158:161], v[68:71]
	v_mfma_f32_16x16x32_bf16 v[64:67], v[120:123], v[158:161], v[64:67]
	v_mfma_f32_16x16x32_bf16 v[158:161], v[112:115], v[16:19], 0
	v_mfma_f32_16x16x32_bf16 v[158:161], v[116:119], v[20:23], v[158:161]
	v_mfma_f32_16x16x32_bf16 v[108:111], v[108:111], v[24:27], 0
	v_mfma_f32_16x16x32_bf16 v[112:115], v[112:115], v[24:27], 0
	s_nop 5
	v_mov_b32_e32 v157, v158
	v_fma_f32 v158, -v172, v210, v159
	v_exp_f32_e32 v198, v158
	v_fma_f32 v158, -v172, v211, v160
	v_exp_f32_e32 v202, v158
	v_fma_f32 v158, -v172, v208, v161
	v_exp_f32_e32 v204, v158
	v_mfma_f32_16x16x32_bf16 v[158:161], v[104:107], v[20:23], v[174:177]
	v_fma_f32 v157, -v172, v209, v157
	v_exp_f32_e32 v157, v157
	v_cndmask_b32_e64 v202, v202, 0, s[6:7]
	v_mfma_f32_16x16x32_bf16 v[104:107], v[104:107], v[28:31], v[108:111]
	v_cndmask_b32_e64 v198, v198, 0, s[18:19]
	s_nop 2
	v_fma_f32 v158, -v172, v212, v158
	v_mfma_f32_16x16x32_bf16 v[112:115], v[116:119], v[28:31], v[112:115]
	v_exp_f32_e32 v158, v158
	v_cndmask_b32_e64 v174, v157, 0, s[14:15]
	v_fma_f32 v104, -v173, v212, v104
	s_nop 2
	v_fma_f32 v157, -v172, v214, v160
	s_nop 0
	v_fma_f32 v113, -v173, v210, v113
	v_exp_f32_e32 v104, v104
	v_fma_f32 v105, -v173, v213, v105
	v_exp_f32_e32 v157, v157
	v_exp_f32_e32 v116, v113
	v_exp_f32_e32 v105, v105
	v_cndmask_b32_e64 v175, v158, 0, s[12:13]
	v_fma_f32 v113, -v173, v211, v114
	v_fma_f32 v159, -v172, v213, v159
	v_fma_f32 v158, -v172, v180, v161
	v_exp_f32_e32 v118, v113
	v_exp_f32_e32 v159, v159
	v_exp_f32_e32 v158, v158
	v_fma_f32 v113, -v173, v208, v115
	v_cndmask_b32_e64 v109, v104, 0, s[12:13]
	v_cndmask_b32_e64 v203, v157, 0, vcc
	v_fma_f32 v112, -v173, v209, v112
	v_exp_f32_e32 v157, v113
	v_cndmask_b32_e64 v113, v105, 0, s[16:17]
	v_fma_f32 v104, -v173, v214, v106
	v_exp_f32_e32 v112, v112
	v_exp_f32_e32 v104, v104
	v_fma_f32 v105, -v173, v180, v107
	v_exp_f32_e32 v105, v105
	v_cndmask_b32_e64 v199, v159, 0, s[16:17]
	v_mul_f32_e32 v160, v146, v202
	v_mul_f32_e32 v161, v147, v203
	v_cndmask_b32_e64 v205, v158, 0, s[8:9]
	v_cndmask_b32_e64 v204, v204, 0, s[10:11]
	v_mul_f32_e32 v176, v146, v174
	v_mul_f32_e32 v177, v147, v175
	v_mul_f32_e32 v200, v146, v198
	v_mul_f32_e32 v201, v147, v199
	v_mul_f32_e32 v206, v146, v204
	v_mul_f32_e32 v207, v147, v205
	v_cvt_pk_bf16_f32 v158, v176, v200
	v_cndmask_b32_e64 v108, v112, 0, s[14:15]
	v_cvt_pk_bf16_f32 v159, v160, v206
	v_cvt_pk_bf16_f32 v160, v177, v201
	v_cvt_pk_bf16_f32 v161, v161, v207
	v_fma_f32 v176, v142, v178, 0
	v_fma_f32 v177, v143, v179, 0
	v_mfma_f32_16x16x32_bf16 v[60:63], v[96:99], v[158:161], v[60:63]
	v_cndmask_b32_e64 v112, v116, 0, s[18:19]
	v_cndmask_b32_e64 v117, v104, 0, vcc
	v_cndmask_b32_e64 v116, v118, 0, s[6:7]
	v_mfma_f32_16x16x32_bf16 v[56:59], v[100:103], v[158:161], v[56:59]
	v_fma_f32 v176, v144, v190, v176
	v_fma_f32 v177, v145, v191, v177
	v_mul_f32_e32 v106, v148, v116
	v_mul_f32_e32 v107, v149, v117
	v_cndmask_b32_e64 v119, v105, 0, s[8:9]
	v_mfma_f32_16x16x32_bf16 v[52:55], v[124:127], v[158:161], v[52:55]
	v_cndmask_b32_e64 v118, v157, 0, s[10:11]
	v_fma_f32 v178, v142, v184, 0
	v_fma_f32 v179, v143, v185, 0
	v_mul_f32_e32 v110, v148, v108
	v_mul_f32_e32 v111, v149, v109
	v_mfma_f32_16x16x32_bf16 v[48:51], v[120:123], v[158:161], v[48:51]
	v_fma_f32 v160, v142, v188, 0
	v_fma_f32 v161, v143, v189, 0
	v_fma_f32 v158, v142, v186, 0
	v_fma_f32 v159, v143, v187, 0
	v_fma_f32 v160, v144, v196, v160
	v_fma_f32 v161, v145, v197, v161
	v_mul_f32_e32 v114, v148, v112
	v_mul_f32_e32 v115, v149, v113
	v_mul_f32_e32 v184, v148, v118
	v_mul_f32_e32 v185, v149, v119
	v_cvt_pk_bf16_f32 v104, v110, v114
	v_fma_f32 v178, v144, v192, v178
	v_fma_f32 v179, v145, v193, v179
	v_cvt_pk_bf16_f32 v105, v106, v184
	v_cvt_pk_bf16_f32 v106, v111, v115
	v_cvt_pk_bf16_f32 v107, v107, v185
	v_fma_f32 v158, v144, v194, v158
	v_fma_f32 v159, v145, v195, v159
	v_mfma_f32_16x16x32_bf16 v[44:47], v[96:99], v[104:107], v[44:47]
	v_fma_f32 v96, v146, v174, v176
	v_fma_f32 v97, v147, v175, v177
	v_fma_f32 v98, v146, v198, v178
	v_fma_f32 v99, v147, v199, v179
	v_fma_f32 v110, v146, v202, v158
	v_fma_f32 v111, v147, v203, v159
	v_mfma_f32_16x16x32_bf16 v[40:43], v[100:103], v[104:107], v[40:43]
	v_fma_f32 v100, v146, v204, v160
	v_fma_f32 v101, v147, v205, v161
	v_fma_f32 v102, v148, v108, v96
	v_fma_f32 v103, v149, v109, v97
	v_fma_f32 v96, v148, v118, v100
	v_fma_f32 v97, v149, v119, v101
	ds_read_b64 v[100:101], v155
	v_fma_f32 v98, v148, v112, v98
	v_fma_f32 v99, v149, v113, v99
	v_fma_f32 v108, v148, v116, v110
	v_fma_f32 v109, v149, v117, v111
	v_add_f32_e32 v98, v102, v98
	v_add_f32_e32 v99, v103, v99
	v_add_f32_e32 v102, v108, v96
	v_add_f32_e32 v103, v109, v97
	v_mfma_f32_16x16x32_bf16 v[36:39], v[124:127], v[104:107], v[36:39]
	v_add_f32_e64 v98, v98, v102
	v_add_f32_e64 v99, v99, v103
	v_cmp_gt_i32_e32 vcc, 63, v156
	s_waitcnt lgkmcnt(0)
	v_add_f32_e32 v98, v98, v100
	v_add_f32_e32 v99, v99, v101
	v_mfma_f32_16x16x32_bf16 v[32:35], v[120:123], v[104:107], v[32:35]
	ds_write_b64 v155, v[98:99]
	s_waitcnt lgkmcnt(0)
	s_and_saveexec_b64 s[6:7], vcc
	s_cbranch_execz .LBB0_383
	ds_read_b32 v98, v155 offset:4
	s_waitcnt lgkmcnt(0)
	v_add_f32_e32 v96, v96, v98
	ds_write_b32 v155, v96 offset:4

.LBB0_398:
	s_lshr_b32 s8, s26, 1
	s_sub_i32 s9, s8, 32
	s_cmp_lt_u32 s26, 64
	s_cselect_b64 vcc, -1, 0
	s_and_b64 s[6:7], vcc, exec
	s_cselect_b32 s6, s8, s9
	v_cndmask_b32_e32 v96, v141, v140, vcc
	s_lshl_b32 s6, 1, s6
	v_and_b32_e32 v96, s6, v96
	v_cmp_ne_u32_e64 s[8:9], 0, v96
	s_mov_b64 vcc, s[8:9]
	s_cbranch_vccz .LBB0_397
	v_add_u32_e32 v152, s1, v130
	s_waitcnt vmcnt(0)
	ds_read_b128 v[124:127], v252 offset:4096
	ds_read_b128 v[120:123], v252 offset:5120
	ds_read_b128 v[116:119], v252 offset:6144
	ds_read_b128 v[112:115], v252 offset:7168
	ds_read_b128 v[108:111], v252 offset:8192
	ds_read_b128 v[104:107], v252 offset:9216
	ds_read_b128 v[100:103], v252 offset:10240
	ds_read_b128 v[96:99], v252 offset:11264
	s_add_i32 s10, s26, 1
	s_lshr_b32 s11, s26, 1
	s_add_i32 s11, s11, 1
	s_lshr_b64 s[12:13], s[98:99], s11
	s_ff1_i32_b64 s14, s[12:13]
	s_cmp_lt_i32 s14, 0
	s_cselect_b32 s14, 0, s14
	s_add_i32 s14, s14, s11
	s_lshl_b32 s14, s14, 1
	s_bitcmp1_b32 s26, 0
	s_cselect_b32 s10, s14, s10
	s_sub_i32 s10, s10, s26
	s_lshl_b32 s10, s10, 12
	s_add_i32 s10, s10, 0xfffff400
	v_add_co_u32_e32 v248, vcc, s10, v138
	s_nop 1
	v_addc_co_u32_e32 v249, vcc, 0, v139, vcc
	v_add_co_u32_e32 v250, vcc, 0xff000000, v248
	s_nop 1
	v_addc_co_u32_e32 v251, vcc, -1, v249, vcc
	v_add_u32_e32 v180, s80, v131
	v_add_u32_e32 v200, -1, v180
	v_add_u32_e32 v204, 2, v152
	v_add_u32_e32 v205, -2, v180
	v_add_u32_e32 v206, 3, v152
	v_cvt_f32_i32_e32 v223, v200
	v_cmp_le_i32_e64 s[12:13], v204, v134
	v_cvt_f32_i32_e32 v224, v205
	v_cmp_le_i32_e64 s[14:15], v206, v134
	v_cmp_le_i32_e32 vcc, v152, v134
	v_cvt_f32_i32_e32 v222, v180
	v_cmp_lt_i32_e64 s[6:7], v152, v134
	v_add_u32_e32 v208, -3, v180
	v_add_u32_e32 v209, 4, v152
	v_add_u32_e32 v210, -4, v180
	v_add_u32_e32 v211, 5, v152
	v_add_u32_e32 v212, -5, v180
	v_add_u32_e32 v213, 6, v152
	v_add_u32_e32 v214, -6, v180
	v_add_u32_e32 v152, 7, v152
	v_add_u32_e32 v180, -7, v180
	v_cvt_f32_i32_e32 v227, v212
	v_cvt_f32_i32_e32 v228, v214
	v_cmp_le_i32_e64 s[24:25], v152, v134
	v_cvt_f32_i32_e32 v152, v180
	v_cmp_le_i32_e64 s[16:17], v209, v134
	v_cmp_le_i32_e64 s[20:21], v211, v134
	v_cmp_le_i32_e64 s[22:23], v213, v134
	s_and_b64 s[18:19], s[8:9], vcc
	s_and_b64 s[10:11], s[8:9], s[6:7]
	s_and_b64 s[12:13], s[8:9], s[12:13]
	s_and_b64 s[14:15], s[8:9], s[14:15]
	s_and_b64 s[16:17], s[8:9], s[16:17]
	s_and_b64 vcc, s[8:9], s[20:21]
	s_and_b64 s[6:7], s[8:9], s[22:23]
	s_and_b64 s[8:9], s[24:25], s[8:9]
	v_cvt_f32_i32_e32 v225, v208
	v_cvt_f32_i32_e32 v226, v210
	s_waitcnt lgkmcnt(0)
	s_add_i32 m0, s79, 0x1000
	s_nop 0
	global_load_lds_dwordx4 v[250:251], off
	global_load_lds_dwordx4 v[250:251], off offset:1024
	global_load_lds_dwordx4 v[250:251], off offset:2048
	global_load_lds_dwordx4 v[250:251], off offset:3072
	s_add_i32 m0, s79, 0x2000
	s_nop 0
	global_load_lds_dwordx4 v[248:249], off
	global_load_lds_dwordx4 v[248:249], off offset:1024
	global_load_lds_dwordx4 v[248:249], off offset:2048
	global_load_lds_dwordx4 v[248:249], off offset:3072
	v_mfma_f32_16x16x32_bf16 v[196:199], v[124:127], v[0:3], 0
	v_mfma_f32_16x16x32_bf16 v[200:203], v[116:119], v[0:3], 0
	v_mfma_f32_16x16x32_bf16 v[204:207], v[124:127], v[8:11], 0
	v_mfma_f32_16x16x32_bf16 v[196:199], v[120:123], v[4:7], v[196:199]
	v_mfma_f32_16x16x32_bf16 v[200:203], v[112:115], v[4:7], v[200:203]
	v_mfma_f32_16x16x32_bf16 v[204:207], v[120:123], v[12:15], v[204:207]
	s_nop 4
	s_nop 0
	v_mov_b32_e32 v180, v196
	v_mov_b32_e32 v196, v197
	v_mov_b32_e32 v197, v198
	v_mov_b32_e32 v198, v199
	v_mov_b32_e32 v199, v200
	v_mov_b32_e32 v200, v201
	v_mov_b32_e32 v201, v202
	v_mov_b32_e32 v202, v203
	v_fma_f32 v200, -v170, v227, v200
	v_fma_f32 v201, -v170, v228, v201
	v_fma_f32 v202, -v170, v152, v202
	v_fma_f32 v203, -v171, v222, v204
	v_exp_f32_e32 v200, v200
	v_exp_f32_e32 v201, v201
	v_exp_f32_e32 v202, v202
	v_exp_f32_e32 v203, v203
	v_fma_f32 v204, -v171, v223, v205
	v_exp_f32_e32 v208, v204
	v_cndmask_b32_e32 v217, 0, v200, vcc
	v_cndmask_b32_e64 v219, 0, v201, s[6:7]
	v_cndmask_b32_e64 v221, 0, v202, s[8:9]
	v_cndmask_b32_e64 v204, 0, v203, s[18:19]
	v_mfma_f32_16x16x32_bf16 v[200:203], v[116:119], v[8:11], 0
	v_fma_f32 v180, -v170, v222, v180
	v_exp_f32_e32 v180, v180
	v_mfma_f32_16x16x32_bf16 v[200:203], v[112:115], v[12:15], v[200:203]
	v_fma_f32 v196, -v170, v223, v196
	v_cndmask_b32_e64 v205, 0, v180, s[18:19]
	v_fma_f32 v180, -v171, v224, v206
	v_exp_f32_e32 v180, v180
	v_fma_f32 v197, -v170, v224, v197
	s_nop 2
	v_fma_f32 v200, -v171, v226, v200
	v_exp_f32_e32 v200, v200
	v_cndmask_b32_e64 v210, 0, v180, s[12:13]
	v_mov_b32_e32 v180, v201
	v_cndmask_b32_e64 v214, 0, v200, s[16:17]
	v_fma_f32 v200, -v171, v228, v202
	v_fma_f32 v201, -v171, v152, v203
	v_fma_f32 v198, -v170, v225, v198
	v_exp_f32_e32 v196, v196
	v_exp_f32_e32 v200, v200
	v_exp_f32_e32 v201, v201
	v_fma_f32 v199, -v170, v226, v199
	v_exp_f32_e32 v197, v197
	v_exp_f32_e32 v198, v198
	v_fma_f32 v206, -v171, v225, v207
	v_exp_f32_e32 v199, v199
	v_exp_f32_e32 v206, v206
	v_fma_f32 v180, -v171, v227, v180
	v_exp_f32_e32 v180, v180
	v_cndmask_b32_e64 v209, 0, v196, s[10:11]
	v_cndmask_b32_e64 v208, 0, v208, s[10:11]
	v_cndmask_b32_e64 v218, 0, v200, s[6:7]
	v_cndmask_b32_e64 v220, 0, v201, s[8:9]
	v_add_f32_e32 v200, 0, v204
	v_add_f32_e32 v201, 0, v205
	v_cndmask_b32_e64 v211, 0, v197, s[12:13]
	v_cndmask_b32_e64 v213, 0, v198, s[14:15]
	v_cvt_pk_bf16_f32 v196, v205, v209
	v_cvt_pk_bf16_f32 v197, v211, v213
	v_add_f32_e32 v200, v208, v200
	v_add_f32_e32 v201, v209, v201
	v_cndmask_b32_e64 v215, 0, v199, s[16:17]
	v_cvt_pk_bf16_f32 v198, v215, v217
	v_cvt_pk_bf16_f32 v199, v219, v221
	v_cndmask_b32_e64 v212, 0, v206, s[14:15]
	s_nop 0
	v_mfma_f32_16x16x32_bf16 v[92:95], v[108:111], v[196:199], v[92:95]
	v_add_f32_e64 v200, v210, v200
	v_add_f32_e64 v201, v211, v201
	v_cndmask_b32_e32 v216, 0, v180, vcc
	v_mfma_f32_16x16x32_bf16 v[88:91], v[104:107], v[196:199], v[88:91]
	v_mfma_f32_16x16x32_bf16 v[84:87], v[100:103], v[196:199], v[84:87]
	v_mfma_f32_16x16x32_bf16 v[80:83], v[96:99], v[196:199], v[80:83]
	v_cvt_pk_bf16_f32 v196, v204, v208
	v_cvt_pk_bf16_f32 v197, v210, v212
	v_cvt_pk_bf16_f32 v198, v214, v216
	v_cvt_pk_bf16_f32 v199, v218, v220
	s_nop 0
	s_nop 0
	v_mfma_f32_16x16x32_bf16 v[76:79], v[108:111], v[196:199], v[76:79]
	v_mfma_f32_16x16x32_bf16 v[72:75], v[104:107], v[196:199], v[72:75]
	v_mfma_f32_16x16x32_bf16 v[68:71], v[100:103], v[196:199], v[68:71]
	v_mfma_f32_16x16x32_bf16 v[64:67], v[96:99], v[196:199], v[64:67]
	v_add_f32_e64 v196, v212, v200
	v_add_f32_e64 v197, v213, v201
	v_add_f32_e32 v196, v214, v196
	v_add_f32_e32 v197, v215, v197
	s_nop 0
	v_add_f32_e32 v200, v216, v196
	v_add_f32_e32 v201, v217, v197
	v_mfma_f32_16x16x32_bf16 v[196:199], v[124:127], v[16:19], 0
	v_add_f32_e64 v200, v218, v200
	v_add_f32_e64 v201, v219, v201
	v_add_f32_e32 v200, v220, v200
	v_add_f32_e32 v201, v221, v201
	v_mfma_f32_16x16x32_bf16 v[196:199], v[120:123], v[20:23], v[196:199]
	v_add_f32_e64 v146, v146, v200
	v_add_f32_e64 v147, v147, v201
	v_mfma_f32_16x16x32_bf16 v[200:203], v[116:119], v[16:19], 0
	v_mfma_f32_16x16x32_bf16 v[124:127], v[124:127], v[24:27], 0
	s_nop 3
	v_mov_b32_e32 v180, v196
	v_fma_f32 v196, -v172, v223, v197
	v_exp_f32_e32 v204, v196
	v_mfma_f32_16x16x32_bf16 v[116:119], v[116:119], v[24:27], 0
	v_fma_f32 v196, -v172, v224, v198
	v_exp_f32_e32 v205, v196
	v_fma_f32 v196, -v172, v225, v199
	v_exp_f32_e32 v206, v196
	v_mfma_f32_16x16x32_bf16 v[196:199], v[112:115], v[20:23], v[200:203]
	v_fma_f32 v180, -v172, v222, v180
	v_exp_f32_e32 v180, v180
	v_cndmask_b32_e64 v205, 0, v205, s[12:13]
	v_mfma_f32_16x16x32_bf16 v[120:123], v[120:123], v[28:31], v[124:127]
	v_cndmask_b32_e64 v203, 0, v204, s[10:11]
	s_nop 2
	v_mfma_f32_16x16x32_bf16 v[112:115], v[112:115], v[28:31], v[116:119]
	s_nop 2
	v_fma_f32 v120, -v173, v222, v120
	v_exp_f32_e32 v120, v120
	s_nop 2
	v_fma_f32 v112, -v173, v226, v112
	v_exp_f32_e32 v112, v112
	v_cndmask_b32_e64 v200, 0, v120, s[18:19]
	v_mov_b32_e32 v120, v121
	v_mov_b32_e32 v121, v122
	v_cndmask_b32_e64 v208, 0, v112, s[16:17]
	v_mov_b32_e32 v112, v113
	v_mov_b32_e32 v113, v114
	v_fma_f32 v196, -v172, v226, v196
	v_fma_f32 v197, -v172, v227, v197
	v_fma_f32 v198, -v172, v228, v198
	v_fma_f32 v199, -v172, v152, v199
	v_fma_f32 v120, -v173, v223, v120
	v_fma_f32 v121, -v173, v224, v121
	v_fma_f32 v122, -v173, v225, v123
	v_fma_f32 v112, -v173, v227, v112
	v_fma_f32 v113, -v173, v228, v113
	v_fma_f32 v114, -v173, v152, v115
	v_exp_f32_e32 v196, v196
	v_exp_f32_e32 v197, v197
	v_exp_f32_e32 v198, v198
	v_exp_f32_e32 v199, v199
	v_exp_f32_e32 v120, v120
	v_exp_f32_e32 v121, v121
	v_exp_f32_e32 v122, v122
	v_exp_f32_e32 v112, v112
	v_exp_f32_e32 v113, v113
	v_exp_f32_e32 v114, v114
	v_cndmask_b32_e64 v201, 0, v180, s[18:19]
	v_cndmask_b32_e64 v207, 0, v206, s[14:15]
	v_cndmask_b32_e64 v209, 0, v196, s[16:17]
	v_cndmask_b32_e32 v211, 0, v197, vcc
	v_cndmask_b32_e64 v213, 0, v198, s[6:7]
	v_cndmask_b32_e64 v215, 0, v199, s[8:9]
	v_cvt_pk_bf16_f32 v196, v201, v203
	v_cvt_pk_bf16_f32 v197, v205, v207
	v_cvt_pk_bf16_f32 v198, v209, v211
	v_cvt_pk_bf16_f32 v199, v213, v215
	v_cndmask_b32_e64 v202, 0, v120, s[10:11]
	v_cndmask_b32_e64 v204, 0, v121, s[12:13]
	v_cndmask_b32_e64 v206, 0, v122, s[14:15]
	v_mfma_f32_16x16x32_bf16 v[60:63], v[108:111], v[196:199], v[60:63]
	v_cndmask_b32_e32 v210, 0, v112, vcc
	v_cndmask_b32_e64 v212, 0, v113, s[6:7]
	v_cndmask_b32_e64 v214, 0, v114, s[8:9]
	v_cvt_pk_bf16_f32 v112, v200, v202
	v_cvt_pk_bf16_f32 v113, v204, v206
	v_cvt_pk_bf16_f32 v114, v208, v210
	v_cvt_pk_bf16_f32 v115, v212, v214
	v_mfma_f32_16x16x32_bf16 v[56:59], v[104:107], v[196:199], v[56:59]
	s_nop 0
	v_mfma_f32_16x16x32_bf16 v[44:47], v[108:111], v[112:115], v[44:47]
	v_add_f32_e64 v108, v200, 0
	v_add_f32_e64 v109, v201, 0
	v_add_f32_e32 v108, v202, v108
	v_add_f32_e32 v109, v203, v109
	v_mfma_f32_16x16x32_bf16 v[40:43], v[104:107], v[112:115], v[40:43]
	v_add_f32_e64 v108, v204, v108
	v_add_f32_e64 v109, v205, v109
	v_add_f32_e32 v104, v206, v108
	v_add_f32_e32 v105, v207, v109
	v_mfma_f32_16x16x32_bf16 v[52:55], v[100:103], v[196:199], v[52:55]
	v_add_f32_e64 v104, v208, v104
	v_add_f32_e64 v105, v209, v105
	v_add_f32_e32 v104, v210, v104
	v_add_f32_e32 v105, v211, v105
	v_mfma_f32_16x16x32_bf16 v[48:51], v[96:99], v[196:199], v[48:51]
	v_mfma_f32_16x16x32_bf16 v[36:39], v[100:103], v[112:115], v[36:39]
	v_add_f32_e64 v100, v212, v104
	v_add_f32_e64 v101, v213, v105
	v_add_f32_e32 v100, v214, v100
	v_add_f32_e32 v101, v215, v101
	v_mfma_f32_16x16x32_bf16 v[32:35], v[96:99], v[112:115], v[32:35]
	v_add_f32_e64 v142, v142, v100
	v_add_f32_e64 v143, v143, v101
	s_branch .LBB0_397

.LBB0_402:
	v_add_u32_e32 v128, -7, v211
	v_add_co_u32_e32 v250, vcc, 0xff000400, v144
	s_nop 1
	v_addc_co_u32_e32 v251, vcc, -1, v145, vcc
	v_add_co_u32_e32 v248, vcc, 0x400, v144
	s_nop 1
	v_addc_co_u32_e32 v249, vcc, 0, v145, vcc
	s_waitcnt vmcnt(0)
	ds_read_b128 v[120:123], v252 offset:4096
	ds_read_b128 v[124:127], v252 offset:5120
	ds_read_b128 v[116:119], v252 offset:6144
	ds_read_b128 v[112:115], v252 offset:7168
	ds_read_b128 v[96:99], v252 offset:8192
	ds_read_b128 v[100:103], v252 offset:9216
	ds_read_b128 v[104:107], v252 offset:10240
	ds_read_b128 v[108:111], v252 offset:11264
	v_add_u32_e32 v129, 7, v210
	v_cmp_le_i32_e32 vcc, v128, v134
	v_cmp_gt_i32_e64 s[6:7], s91, v129
	s_and_b64 s[12:13], vcc, s[6:7]
	v_cmp_lt_i32_e32 vcc, v128, v134
	v_add_u32_e32 v128, 6, v210
	v_cmp_gt_i32_e64 s[6:7], s91, v128
	v_cvt_f32_i32_e32 v150, v128
	v_add_u32_e32 v128, -5, v211
	s_and_b64 s[14:15], vcc, s[6:7]
	v_cmp_le_i32_e32 vcc, v128, v134
	v_add_u32_e32 v128, 5, v210
	v_cmp_gt_i32_e64 s[6:7], s91, v128
	v_cvt_f32_i32_e32 v158, v128
	v_add_u32_e32 v128, -4, v211
	s_and_b64 s[16:17], vcc, s[6:7]
	v_cmp_le_i32_e32 vcc, v128, v134
	v_add_u32_e32 v128, 4, v210
	v_cmp_gt_i32_e64 s[6:7], s91, v128
	v_cvt_f32_i32_e32 v212, v128
	v_add_u32_e32 v128, -3, v211
	s_and_b64 s[18:19], vcc, s[6:7]
	v_cmp_le_i32_e32 vcc, v128, v134
	v_add_u32_e32 v128, 3, v210
	v_cmp_gt_i32_e64 s[6:7], s91, v128
	v_cvt_f32_i32_e32 v148, v128
	v_add_u32_e32 v128, -2, v211
	s_and_b64 s[10:11], vcc, s[6:7]
	v_cmp_le_i32_e32 vcc, v128, v134
	v_add_u32_e32 v128, 2, v210
	v_cmp_gt_i32_e64 s[6:7], s91, v128
	v_cvt_f32_i32_e32 v154, v128
	v_add_u32_e32 v128, -1, v211
	s_and_b64 s[8:9], vcc, s[6:7]
	v_cmp_le_i32_e32 vcc, v128, v134
	v_add_u32_e32 v128, 1, v210
	v_cvt_f32_i32_e32 v146, v129
	v_cmp_gt_i32_e64 s[6:7], s91, v128
	v_cvt_f32_i32_e32 v152, v128
	v_cvt_f32_i32_e32 v132, v210
	s_and_b64 s[6:7], vcc, s[6:7]
	v_cmp_le_i32_e32 vcc, v211, v134
	v_cmp_gt_i32_e64 s[20:21], s91, v210
	s_and_b64 vcc, vcc, s[20:21]
	s_add_i32 s0, s0, 1
	v_subrev_u32_e32 v210, 32, v210
	v_add_u32_e32 v211, 32, v211
	v_lshl_add_u64 v[144:145], v[144:145], 0, s[52:53]
	s_cmp_lt_u32 s0, s71
	s_waitcnt lgkmcnt(0)
	s_mov_b32 m0, s98
	s_nop 0
	global_load_lds_dwordx4 v[250:251], off
	global_load_lds_dwordx4 v[250:251], off offset:1024
	global_load_lds_dwordx4 v[250:251], off offset:2048
	global_load_lds_dwordx4 v[250:251], off offset:3072
	s_mov_b32 m0, s99
	s_nop 0
	global_load_lds_dwordx4 v[248:249], off
	global_load_lds_dwordx4 v[248:249], off offset:1024
	global_load_lds_dwordx4 v[248:249], off offset:2048
	global_load_lds_dwordx4 v[248:249], off offset:3072
	v_mfma_f32_16x16x32_bf16 v[128:131], v[120:123], v[0:3], 0
	v_mfma_f32_16x16x32_bf16 v[128:131], v[124:127], v[4:7], v[128:131]
	v_mfma_f32_16x16x32_bf16 v[214:217], v[120:123], v[8:11], 0
	v_mfma_f32_16x16x32_bf16 v[214:217], v[124:127], v[12:15], v[214:217]
	s_nop 5
	v_fma_f32 v128, -v170, v146, v128
	v_exp_f32_e32 v147, v128
	v_fma_f32 v128, -v170, v150, v129
	v_exp_f32_e32 v149, v128
	v_cndmask_b32_e64 v157, 0, v147, s[12:13]
	v_fma_f32 v147, -v171, v146, v214
	v_exp_f32_e32 v147, v147
	v_fma_f32 v128, -v170, v158, v130
	v_exp_f32_e32 v151, v128
	v_cndmask_b32_e64 v156, 0, v147, s[12:13]
	v_fma_f32 v147, -v171, v150, v215
	v_exp_f32_e32 v147, v147
	v_fma_f32 v128, -v170, v212, v131
	v_exp_f32_e32 v153, v128
	v_cndmask_b32_e64 v160, 0, v147, s[14:15]
	v_fma_f32 v147, -v171, v158, v216
	v_exp_f32_e32 v147, v147
	v_cndmask_b32_e64 v161, 0, v149, s[14:15]
	v_add_f32_e32 v230, 0, v156
	v_add_f32_e32 v231, 0, v157
	v_cndmask_b32_e64 v219, 0, v151, s[16:17]
	v_cndmask_b32_e64 v218, 0, v147, s[16:17]
	v_fma_f32 v147, -v171, v212, v217
	v_exp_f32_e32 v147, v147
	v_add_f32_e32 v214, v160, v230
	v_add_f32_e32 v215, v161, v231
	v_cndmask_b32_e64 v221, 0, v153, s[18:19]
	v_add_f32_e32 v214, v218, v214
	v_add_f32_e32 v215, v219, v215
	v_cndmask_b32_e64 v220, 0, v147, s[18:19]
	v_add_f32_e32 v230, v220, v214
	v_add_f32_e32 v231, v221, v215
	v_mfma_f32_16x16x32_bf16 v[214:217], v[116:119], v[8:11], 0
	v_mfma_f32_16x16x32_bf16 v[214:217], v[112:115], v[12:15], v[214:217]
	v_mfma_f32_16x16x32_bf16 v[128:131], v[116:119], v[0:3], 0
	v_mfma_f32_16x16x32_bf16 v[128:131], v[112:115], v[4:7], v[128:131]
	s_nop 5
	v_fma_f32 v147, -v171, v148, v214
	v_exp_f32_e32 v147, v147
	s_nop 0
	v_cndmask_b32_e64 v222, 0, v147, s[10:11]
	v_fma_f32 v147, -v171, v154, v215
	v_exp_f32_e32 v147, v147
	s_nop 0
	v_cndmask_b32_e64 v224, 0, v147, s[8:9]
	v_fma_f32 v147, -v171, v152, v216
	v_exp_f32_e32 v147, v147
	v_fma_f32 v128, -v170, v148, v128
	v_fma_f32 v129, -v170, v154, v129
	v_fma_f32 v130, -v170, v152, v130
	v_fma_f32 v131, -v170, v132, v131
	v_cndmask_b32_e64 v226, 0, v147, s[6:7]
	v_exp_f32_e32 v128, v128
	v_exp_f32_e32 v129, v129
	v_exp_f32_e32 v130, v130
	v_exp_f32_e32 v131, v131
	v_fma_f32 v147, -v171, v132, v217
	v_exp_f32_e32 v147, v147
	v_cndmask_b32_e64 v223, 0, v128, s[10:11]
	v_cndmask_b32_e64 v225, 0, v129, s[8:9]
	v_cndmask_b32_e64 v227, 0, v130, s[6:7]
	v_cndmask_b32_e32 v229, 0, v131, vcc
	v_cvt_pk_bf16_f32 v128, v157, v161
	v_cvt_pk_bf16_f32 v129, v219, v221
	v_cvt_pk_bf16_f32 v130, v223, v225
	v_cvt_pk_bf16_f32 v131, v227, v229
	v_cndmask_b32_e32 v228, 0, v147, vcc
	s_nop 0
	v_mfma_f32_16x16x32_bf16 v[80:83], v[96:99], v[128:131], v[80:83]
	v_add_f32_e64 v230, v222, v230
	v_add_f32_e64 v231, v223, v231
	v_add_f32_e32 v214, v224, v230
	v_add_f32_e32 v215, v225, v231
	v_mfma_f32_16x16x32_bf16 v[84:87], v[100:103], v[128:131], v[84:87]
	v_add_f32_e64 v214, v226, v214
	v_add_f32_e64 v215, v227, v215
	v_add_f32_e32 v214, v228, v214
	v_add_f32_e32 v215, v229, v215
	v_mfma_f32_16x16x32_bf16 v[88:91], v[104:107], v[128:131], v[88:91]
	v_add_f32_e64 v138, v138, v214
	v_add_f32_e64 v139, v139, v215
	v_mfma_f32_16x16x32_bf16 v[92:95], v[108:111], v[128:131], v[92:95]
	v_cvt_pk_bf16_f32 v128, v156, v160
	v_cvt_pk_bf16_f32 v129, v218, v220
	v_cvt_pk_bf16_f32 v130, v222, v224
	v_cvt_pk_bf16_f32 v131, v226, v228
	s_nop 0
	s_nop 0
	v_mfma_f32_16x16x32_bf16 v[64:67], v[96:99], v[128:131], v[64:67]
	v_mfma_f32_16x16x32_bf16 v[68:71], v[100:103], v[128:131], v[68:71]
	v_mfma_f32_16x16x32_bf16 v[72:75], v[104:107], v[128:131], v[72:75]
	v_mfma_f32_16x16x32_bf16 v[76:79], v[108:111], v[128:131], v[76:79]
	v_mfma_f32_16x16x32_bf16 v[128:131], v[120:123], v[16:19], 0
	v_mfma_f32_16x16x32_bf16 v[128:131], v[124:127], v[20:23], v[128:131]
	v_mfma_f32_16x16x32_bf16 v[120:123], v[120:123], v[24:27], 0
	v_mfma_f32_16x16x32_bf16 v[120:123], v[124:127], v[28:31], v[120:123]
	s_nop 5
	v_fma_f32 v128, -v172, v146, v128
	v_exp_f32_e32 v147, v128
	v_fma_f32 v128, -v172, v150, v129
	v_exp_f32_e32 v149, v128
	v_fma_f32 v128, -v172, v158, v130
	v_exp_f32_e32 v151, v128
	v_fma_f32 v128, -v172, v212, v131
	v_exp_f32_e32 v153, v128
	v_mfma_f32_16x16x32_bf16 v[128:131], v[116:119], v[16:19], 0
	v_fma_f32 v120, -v173, v146, v120
	v_exp_f32_e32 v120, v120
	v_mfma_f32_16x16x32_bf16 v[116:119], v[116:119], v[24:27], 0
	v_fma_f32 v122, -v173, v158, v122
	v_exp_f32_e32 v122, v122
	v_mfma_f32_16x16x32_bf16 v[128:131], v[112:115], v[20:23], v[128:131]
	v_cndmask_b32_e64 v156, 0, v120, s[12:13]
	v_fma_f32 v120, -v173, v150, v121
	v_mfma_f32_16x16x32_bf16 v[112:115], v[112:115], v[28:31], v[116:119]
	v_exp_f32_e32 v120, v120
	v_cndmask_b32_e64 v146, 0, v122, s[16:17]
	s_nop 0
	v_fma_f32 v122, -v173, v212, v123
	s_nop 1
	s_nop 1
	v_fma_f32 v112, -v173, v148, v112
	v_exp_f32_e32 v112, v112
	v_fma_f32 v114, -v173, v152, v114
	v_exp_f32_e32 v114, v114
	v_fma_f32 v128, -v172, v148, v128
	v_exp_f32_e32 v122, v122
	v_cndmask_b32_e64 v148, 0, v112, s[10:11]
	v_exp_f32_e32 v128, v128
	v_fma_f32 v129, -v172, v154, v129
	v_cndmask_b32_e64 v157, 0, v147, s[12:13]
	v_fma_f32 v112, -v173, v154, v113
	v_exp_f32_e32 v129, v129
	v_fma_f32 v130, -v172, v152, v130
	v_cndmask_b32_e64 v161, 0, v149, s[14:15]
	v_add_f32_e32 v124, 0, v156
	v_add_f32_e32 v125, 0, v157
	v_cndmask_b32_e64 v160, 0, v120, s[14:15]
	v_exp_f32_e32 v112, v112
	v_cndmask_b32_e64 v152, 0, v114, s[6:7]
	v_exp_f32_e32 v130, v130
	v_fma_f32 v131, -v172, v132, v131
	v_cndmask_b32_e64 v147, 0, v151, s[16:17]
	v_add_f32_e32 v120, v160, v124
	v_add_f32_e32 v121, v161, v125
	v_fma_f32 v114, -v173, v132, v115
	v_exp_f32_e32 v131, v131
	v_cndmask_b32_e64 v151, 0, v153, s[18:19]
	v_add_f32_e32 v120, v146, v120
	v_add_f32_e32 v121, v147, v121
	v_cndmask_b32_e64 v150, 0, v122, s[18:19]
	v_exp_f32_e32 v114, v114
	v_cndmask_b32_e64 v149, 0, v128, s[10:11]
	v_add_f32_e32 v120, v150, v120
	v_add_f32_e32 v121, v151, v121
	v_cndmask_b32_e64 v155, 0, v129, s[8:9]
	v_add_f32_e32 v116, v148, v120
	v_add_f32_e32 v117, v149, v121
	v_cndmask_b32_e64 v154, 0, v112, s[8:9]
	v_cndmask_b32_e64 v153, 0, v130, s[6:7]
	v_add_f32_e32 v112, v154, v116
	v_add_f32_e32 v113, v155, v117
	v_cndmask_b32_e32 v159, 0, v131, vcc
	v_add_f32_e32 v112, v152, v112
	v_add_f32_e32 v113, v153, v113
	v_cndmask_b32_e32 v158, 0, v114, vcc
	v_add_f32_e32 v112, v158, v112
	v_add_f32_e32 v113, v159, v113
	v_cvt_pk_bf16_f32 v128, v157, v161
	v_cvt_pk_bf16_f32 v129, v147, v151
	v_cvt_pk_bf16_f32 v130, v149, v155
	v_cvt_pk_bf16_f32 v131, v153, v159
	v_cvt_pk_bf16_f32 v114, v148, v154
	s_nop 0
	v_add_f32_e32 v142, v142, v112
	v_add_f32_e32 v143, v143, v113
	v_mfma_f32_16x16x32_bf16 v[48:51], v[96:99], v[128:131], v[48:51]
	v_cvt_pk_bf16_f32 v112, v156, v160
	v_cvt_pk_bf16_f32 v113, v146, v150
	v_cvt_pk_bf16_f32 v115, v152, v158
	v_mfma_f32_16x16x32_bf16 v[52:55], v[100:103], v[128:131], v[52:55]
	v_mfma_f32_16x16x32_bf16 v[56:59], v[104:107], v[128:131], v[56:59]
	v_mfma_f32_16x16x32_bf16 v[60:63], v[108:111], v[128:131], v[60:63]
	v_mfma_f32_16x16x32_bf16 v[32:35], v[96:99], v[112:115], v[32:35]
	v_mfma_f32_16x16x32_bf16 v[36:39], v[100:103], v[112:115], v[36:39]
	v_mfma_f32_16x16x32_bf16 v[44:47], v[104:107], v[112:115], v[44:47]
	v_mfma_f32_16x16x32_bf16 v[40:43], v[108:111], v[112:115], v[40:43]
	s_cbranch_scc1 .LBB0_402
	s_branch .LBB0_369
